# UP epilogue: halo export stores merged 4->1 via DPP row shifts (32->8 store instructions per unit)
# speedup vs baseline: 1.0103x; 1.0103x over previous
.LBB0_216:
	s_lshl_b32 s23, s34, 8
	s_add_i32 s23, s23, s54
	v_or_b32_e32 v237, s23, v231
	v_lshl_or_b32 v0, v237, 6, v193
	v_or_b32_e32 v240, 1, v237
	v_lshl_add_u64 v[70:71], s[10:11], 0, v[0:1]
	v_lshl_or_b32 v72, v240, 6, v193
	v_mov_b32_e32 v73, v1
	v_lshl_add_u64 v[72:73], s[10:11], 0, v[72:73]
	global_load_dwordx4 v[166:169], v[70:71], off
	global_load_dwordx4 v[170:173], v[72:73], off
	v_or_b32_e32 v239, 2, v237
	v_lshl_or_b32 v70, v239, 6, v193
	v_mov_b32_e32 v71, v1
	v_lshl_add_u64 v[70:71], s[10:11], 0, v[70:71]
	global_load_dwordx4 v[174:177], v[70:71], off
	v_or_b32_e32 v70, 0xc0, v0
	v_mov_b32_e32 v71, v1
	v_lshl_add_u64 v[70:71], s[10:11], 0, v[70:71]
	global_load_dwordx4 v[178:181], v[70:71], off
	v_add_u32_e32 v238, 0x80, v237
	v_mov_b32_e32 v71, v1
	v_lshl_or_b32 v70, v238, 6, v193
	v_lshl_add_u64 v[70:71], s[10:11], 0, v[70:71]
	global_load_dwordx4 v[242:245], v[70:71], off
	v_mov_b32_e32 v73, v1
	v_mov_b32_e32 v75, v1
	v_lshl_or_b32 v192, s30, 7, v235
	v_add_u32_e32 v72, 0x2040, v0
	v_add_u32_e32 v74, 0x2080, v0
	v_add_u32_e32 v0, 0x20c0, v0
	v_lshl_add_u64 v[72:73], s[10:11], 0, v[72:73]
	v_lshl_add_u64 v[70:71], s[10:11], 0, v[74:75]
	v_lshl_add_u64 v[74:75], s[10:11], 0, v[0:1]
	v_lshlrev_b32_e32 v0, 2, v192
	global_load_dwordx4 v[246:249], v[72:73], off
	global_load_dwordx4 v[250:253], v[70:71], off
	global_load_dwordx4 v[194:197], v[74:75], off
	v_lshl_add_u64 v[206:207], s[12:13], 0, v[0:1]
	s_movk_i32 s25, 0x6000
	v_add_co_u32_e32 v202, vcc, s25, v206
	s_mov_b32 s25, 0xc000
	s_nop 0
	v_addc_co_u32_e32 v203, vcc, 0, v207, vcc
	v_add_co_u32_e32 v208, vcc, s25, v206
	s_movk_i32 s25, 0x3000
	s_nop 0
	v_addc_co_u32_e32 v209, vcc, 0, v207, vcc
	v_add_co_u32_e32 v204, vcc, s25, v206
	s_mov_b32 s30, 0x9000
	s_nop 0
	v_addc_co_u32_e32 v205, vcc, 0, v207, vcc
	v_add_co_u32_e32 v210, vcc, s30, v206
	s_mov_b32 s30, 0xf000
	s_nop 0
	v_addc_co_u32_e32 v211, vcc, 0, v207, vcc
	v_add_co_u32_e32 v212, vcc, s30, v206
	v_lshl_add_u64 v[200:201], s[14:15], 0, v[0:1]
	s_nop 0
	v_addc_co_u32_e32 v213, vcc, 0, v207, vcc
	v_add_co_u32_e32 v214, vcc, s25, v200
	global_load_dwordx4 v[74:77], v[206:207], off
	global_load_dwordx4 v[78:81], v[200:201], off
	v_addc_co_u32_e32 v215, vcc, 0, v201, vcc
	global_load_dwordx4 v[98:101], v[202:203], off
	global_load_dwordx4 v[94:97], v[208:209], off
	global_load_dwordx4 v[86:89], v[204:205], off
	global_load_dwordx4 v[82:85], v[210:211], off
	global_load_dwordx4 v[70:73], v[212:213], off
	global_load_dwordx4 v[90:93], v[214:215], off
	s_waitcnt vmcnt(0) lgkmcnt(0)
	v_mov_b32_e32 v216, v167
	v_mov_b32_e32 v217, v168
	v_mov_b32_e32 v167, v169
	v_pk_add_f32 v[166:167], v[216:217], v[166:167]
	v_mov_b32_e32 v168, v171
	v_mov_b32_e32 v169, v172
	v_mov_b32_e32 v171, v173
	v_add_f32_e32 v0, v166, v167
	v_pk_add_f32 v[166:167], v[168:169], v[170:171]
	ds_bpermute_b32 v170, v233, v0
	v_mov_b32_e32 v172, v175
	v_mov_b32_e32 v173, v176
	v_mov_b32_e32 v175, v177
	v_mov_b32_e32 v176, v179
	v_mov_b32_e32 v177, v180
	v_pk_add_f32 v[168:169], v[172:173], v[174:175]
	v_mov_b32_e32 v179, v181
	v_add_f32_e32 v173, v168, v169
	v_pk_add_f32 v[168:169], v[176:177], v[178:179]
	v_add_f32_e32 v171, v166, v167
	s_waitcnt lgkmcnt(0)
	v_add_f32_e32 v166, v0, v170
	v_add_f32_e32 v0, v168, v169
	ds_bpermute_b32 v174, v233, v173
	ds_bpermute_b32 v175, v233, v0
	v_mov_b32_e32 v168, v243
	v_mov_b32_e32 v169, v244
	v_mov_b32_e32 v243, v245
	v_pk_add_f32 v[168:169], v[168:169], v[242:243]
	s_waitcnt lgkmcnt(0)
	v_add_f32_e32 v0, v0, v175
	v_add_f32_e32 v176, v168, v169
	ds_bpermute_b32 v177, v233, v176
	v_add_f32_e32 v169, v173, v174
	v_mov_b32_e32 v174, v247
	v_mov_b32_e32 v175, v248
	v_mov_b32_e32 v247, v249
	v_pk_add_f32 v[174:175], v[174:175], v[246:247]
	s_waitcnt lgkmcnt(0)
	v_add_f32_e32 v243, v176, v177
	v_add_f32_e32 v173, v174, v175
	v_mov_b32_e32 v174, v251
	v_mov_b32_e32 v175, v252
	v_mov_b32_e32 v251, v253
	v_pk_add_f32 v[174:175], v[174:175], v[250:251]
	ds_bpermute_b32 v172, v233, v171
	v_add_f32_e32 v177, v174, v175
	v_mov_b32_e32 v174, v195
	v_mov_b32_e32 v175, v196
	v_mov_b32_e32 v195, v197
	v_pk_add_f32 v[174:175], v[174:175], v[194:195]
	ds_bpermute_b32 v176, v233, v173
	v_add_f32_e32 v174, v174, v175
	ds_bpermute_b32 v178, v233, v177
	ds_bpermute_b32 v175, v233, v174
	s_waitcnt lgkmcnt(3)
	v_add_f32_e32 v170, v171, v172
	s_waitcnt lgkmcnt(2)
	v_add_f32_e32 v241, v173, v176
	ds_bpermute_b32 v167, v234, v166
	s_waitcnt lgkmcnt(2)
	v_add_f32_e32 v247, v177, v178
	s_waitcnt lgkmcnt(1)
	v_add_f32_e32 v245, v174, v175
	ds_bpermute_b32 v171, v234, v170
	ds_bpermute_b32 v244, v234, v243
	ds_bpermute_b32 v242, v234, v241
	ds_bpermute_b32 v248, v234, v247
	ds_bpermute_b32 v246, v234, v245
	ds_bpermute_b32 v172, v234, v169
	ds_bpermute_b32 v168, v234, v0
	s_waitcnt lgkmcnt(1)
	v_add_f32_e32 v169, v169, v172
	s_waitcnt lgkmcnt(0)
	v_add_f32_e32 v0, v0, v168
	v_fmamk_f32 v169, v169, 0x3a800000, v219
	v_fmamk_f32 v0, v0, 0x3a800000, v219
	v_rsq_f32_e32 v172, v169
	v_rsq_f32_e32 v0, v0
	s_lshr_b32 s25, s23, 4
	v_cmp_lt_i32_e32 vcc, 11, v5
	v_pk_mul_f32 v[152:153], v[152:153], v[172:173] op_sel_hi:[1,0]
	v_pk_mul_f32 v[150:151], v[150:151], v[172:173] op_sel_hi:[1,0]
	v_pk_mul_f32 v[24:25], v[24:25], v[172:173] op_sel_hi:[1,0]
	v_pk_mul_f32 v[22:23], v[22:23], v[172:173] op_sel_hi:[1,0]
	v_pk_mul_f32 v[148:149], v[148:149], v[172:173] op_sel_hi:[1,0]
	v_pk_mul_f32 v[146:147], v[146:147], v[172:173] op_sel_hi:[1,0]
	v_pk_mul_f32 v[20:21], v[20:21], v[172:173] op_sel_hi:[1,0]
	v_pk_mul_f32 v[18:19], v[18:19], v[172:173] op_sel_hi:[1,0]
	v_pk_mul_f32 v[164:165], v[164:165], v[0:1] op_sel_hi:[1,0]
	v_pk_mul_f32 v[162:163], v[162:163], v[0:1] op_sel_hi:[1,0]
	v_pk_mul_f32 v[36:37], v[36:37], v[0:1] op_sel_hi:[1,0]
	v_pk_mul_f32 v[34:35], v[34:35], v[0:1] op_sel_hi:[1,0]
	v_pk_mul_f32 v[160:161], v[160:161], v[0:1] op_sel_hi:[1,0]
	v_pk_mul_f32 v[158:159], v[158:159], v[0:1] op_sel_hi:[1,0]
	v_pk_mul_f32 v[32:33], v[32:33], v[0:1] op_sel_hi:[1,0]
	v_pk_mul_f32 v[30:31], v[30:31], v[0:1] op_sel_hi:[1,0]
	v_sub_u32_e32 v255, 15, v5
	v_min_u32_e32 v255, v255, v5
	v_and_b32_e32 v0, 1, v255
	v_lshrrev_b32_e32 v255, 1, v255
	v_mul_u32_u24_e32 v255, 0x3000, v255
	v_lshl_add_u32 v255, v0, 4, v255
	s_mov_b64 s[30:31], 0
	s_and_saveexec_b64 s[34:35], vcc
	s_xor_b64 s[34:35], exec, s[34:35]
	v_readlane_b32 s43, v254, 41
	v_readlane_b32 s42, v254, 42
	s_cbranch_execz .LBB0_222
	s_and_b32 s37, s23, 0xfc0
	s_cmpk_eq_i32 s37, 0xfc0
	s_cselect_b64 s[30:31], -1, 0
	s_lshr_b32 s36, s23, 11
	s_cmpk_lg_i32 s37, 0xfc0
	s_mul_i32 s37, s25, 0x1800
	v_add_u32_e32 v168, s37, v192
	v_lshl_add_u32 v0, v168, 2, v225
	v_add_u32_e32 v0, v0, v255
	v_lshl_add_u64 v[172:173], s[16:17], 0, v[0:1]
	v_mov_b32_e32 v178, v150
	v_mov_b32_e32 v179, v151
	v_mov_b32_e32 v180, v152
	v_mov_b32_e32 v181, v153
	v_mov_b32_dpp v178, v22 row_shl:1 row_mask:0xf bank_mask:0x8
	v_mov_b32_dpp v179, v23 row_shl:1 row_mask:0xf bank_mask:0x8
	v_mov_b32_dpp v180, v24 row_shl:1 row_mask:0xf bank_mask:0x8
	v_mov_b32_dpp v181, v25 row_shl:1 row_mask:0xf bank_mask:0x8
	v_mov_b32_dpp v178, v146 row_shl:2 row_mask:0xf bank_mask:0x8
	v_mov_b32_dpp v179, v147 row_shl:2 row_mask:0xf bank_mask:0x8
	v_mov_b32_dpp v180, v148 row_shl:2 row_mask:0xf bank_mask:0x8
	v_mov_b32_dpp v181, v149 row_shl:2 row_mask:0xf bank_mask:0x8
	v_mov_b32_dpp v178, v18 row_shl:3 row_mask:0xf bank_mask:0x8
	v_mov_b32_dpp v179, v19 row_shl:3 row_mask:0xf bank_mask:0x8
	v_mov_b32_dpp v180, v20 row_shl:3 row_mask:0xf bank_mask:0x8
	v_mov_b32_dpp v181, v21 row_shl:3 row_mask:0xf bank_mask:0x8
	global_store_dwordx4 v[172:173], v[178:181], off
	s_cbranch_scc1 .LBB0_219
	s_and_b32 s37, s36, 0x1ffffe
	s_mulk_i32 s37, 0x1800
	v_add_lshl_u32 v0, s37, v192, 2
	v_add_u32_e32 v0, v0, v255
	v_lshl_add_u64 v[172:173], s[18:19], 0, v[0:1]
	global_store_dwordx4 v[172:173], v[178:181], off
.LBB0_219:
	v_lshl_add_u32 v0, v168, 2, v226
	v_add_u32_e32 v0, v0, v255
	v_lshl_add_u64 v[168:169], s[16:17], 0, v[0:1]
	v_mov_b32_e32 v178, v162
	v_mov_b32_e32 v179, v163
	v_mov_b32_e32 v180, v164
	v_mov_b32_e32 v181, v165
	v_mov_b32_dpp v178, v34 row_shl:1 row_mask:0xf bank_mask:0x8
	v_mov_b32_dpp v179, v35 row_shl:1 row_mask:0xf bank_mask:0x8
	v_mov_b32_dpp v180, v36 row_shl:1 row_mask:0xf bank_mask:0x8
	v_mov_b32_dpp v181, v37 row_shl:1 row_mask:0xf bank_mask:0x8
	v_mov_b32_dpp v178, v158 row_shl:2 row_mask:0xf bank_mask:0x8
	v_mov_b32_dpp v179, v159 row_shl:2 row_mask:0xf bank_mask:0x8
	v_mov_b32_dpp v180, v160 row_shl:2 row_mask:0xf bank_mask:0x8
	v_mov_b32_dpp v181, v161 row_shl:2 row_mask:0xf bank_mask:0x8
	v_mov_b32_dpp v178, v30 row_shl:3 row_mask:0xf bank_mask:0x8
	v_mov_b32_dpp v179, v31 row_shl:3 row_mask:0xf bank_mask:0x8
	v_mov_b32_dpp v180, v32 row_shl:3 row_mask:0xf bank_mask:0x8
	v_mov_b32_dpp v181, v33 row_shl:3 row_mask:0xf bank_mask:0x8
	global_store_dwordx4 v[168:169], v[178:181], off
	s_andn2_b64 vcc, exec, s[30:31]
	s_mov_b64 s[30:31], 0
	s_cbranch_vccnz .LBB0_221
	s_mulk_i32 s36, 0x1800
	v_add_u32_e32 v0, s36, v192
	s_mov_b64 s[30:31], -1

.LBB0_222:
	s_or_saveexec_b64 s[34:35], s[34:35]
	v_add_f32_e32 v166, v166, v167
	v_fmamk_f32 v166, v166, 0x3a800000, v219
	v_rsq_f32_e32 v172, v166
	v_mov_b64_e32 v[176:177], v[36:37]
	v_mov_b64_e32 v[180:181], v[164:165]
	v_mov_b64_e32 v[216:217], s[18:19]
	v_pk_mul_f32 v[168:169], v[156:157], v[172:173] op_sel_hi:[1,0]
	v_pk_mul_f32 v[156:157], v[68:69], v[172:173] op_sel_hi:[1,0]
	v_add_f32_e32 v68, v170, v171
	v_fmamk_f32 v68, v68, 0x3a800000, v219
	v_rsq_f32_e32 v170, v68
	v_pk_mul_f32 v[166:167], v[154:155], v[172:173] op_sel_hi:[1,0]
	v_pk_mul_f32 v[60:61], v[60:61], v[172:173] op_sel_hi:[1,0]
	v_pk_mul_f32 v[58:59], v[58:59], v[172:173] op_sel_hi:[1,0]
	v_pk_mul_f32 v[154:155], v[66:67], v[172:173] op_sel_hi:[1,0]
	v_pk_mul_f32 v[56:57], v[56:57], v[172:173] op_sel_hi:[1,0]
	v_pk_mul_f32 v[54:55], v[54:55], v[172:173] op_sel_hi:[1,0]
	v_pk_mul_f32 v[144:145], v[144:145], v[170:171] op_sel_hi:[1,0]
	v_pk_mul_f32 v[142:143], v[142:143], v[170:171] op_sel_hi:[1,0]
	v_pk_mul_f32 v[68:69], v[140:141], v[170:171] op_sel_hi:[1,0]
	v_pk_mul_f32 v[66:67], v[138:139], v[170:171] op_sel_hi:[1,0]
	v_pk_mul_f32 v[140:141], v[136:137], v[170:171] op_sel_hi:[1,0]
	v_pk_mul_f32 v[138:139], v[134:135], v[170:171] op_sel_hi:[1,0]
	v_pk_mul_f32 v[64:65], v[64:65], v[170:171] op_sel_hi:[1,0]
	v_pk_mul_f32 v[62:63], v[62:63], v[170:171] op_sel_hi:[1,0]
	v_mov_b64_e32 v[136:137], v[32:33]
	v_mov_b64_e32 v[172:173], v[160:161]
	v_mov_b64_e32 v[134:135], v[30:31]
	v_mov_b64_e32 v[170:171], v[158:159]
	v_mov_b64_e32 v[174:175], v[34:35]
	v_mov_b64_e32 v[178:179], v[162:163]
	s_xor_b64 exec, exec, s[34:35]
	s_cbranch_execz .LBB0_226
	v_cmp_gt_u32_e32 vcc, 4, v5
	s_mov_b64 s[38:39], s[30:31]
	s_and_saveexec_b64 s[36:37], vcc
	s_cbranch_execz .LBB0_225
	s_mulk_i32 s25, 0x1800
	v_add_u32_e32 v136, s25, v192
	v_lshl_add_u32 v0, v136, 2, v255
	v_lshl_add_u64 v[134:135], s[16:17], 0, v[0:1]
	v_mov_b32_e32 v194, v166
	v_mov_b32_e32 v195, v167
	v_mov_b32_e32 v196, v168
	v_mov_b32_e32 v197, v169
	v_mov_b32_dpp v194, v58 row_shr:1 row_mask:0xf bank_mask:0x1
	v_mov_b32_dpp v195, v59 row_shr:1 row_mask:0xf bank_mask:0x1
	v_mov_b32_dpp v196, v60 row_shr:1 row_mask:0xf bank_mask:0x1
	v_mov_b32_dpp v197, v61 row_shr:1 row_mask:0xf bank_mask:0x1
	v_mov_b32_dpp v194, v154 row_shr:2 row_mask:0xf bank_mask:0x1
	v_mov_b32_dpp v195, v155 row_shr:2 row_mask:0xf bank_mask:0x1
	v_mov_b32_dpp v196, v156 row_shr:2 row_mask:0xf bank_mask:0x1
	v_mov_b32_dpp v197, v157 row_shr:2 row_mask:0xf bank_mask:0x1
	v_mov_b32_dpp v194, v54 row_shr:3 row_mask:0xf bank_mask:0x1
	v_mov_b32_dpp v195, v55 row_shr:3 row_mask:0xf bank_mask:0x1
	v_mov_b32_dpp v196, v56 row_shr:3 row_mask:0xf bank_mask:0x1
	v_mov_b32_dpp v197, v57 row_shr:3 row_mask:0xf bank_mask:0x1
	v_add_u32_e32 v0, 0x1800, v136
	s_or_b64 s[38:39], s[30:31], exec
	global_store_dwordx4 v[134:135], v[194:197], off

.LBB0_226:
	s_or_b64 exec, exec, s[34:35]
	s_and_saveexec_b64 s[34:35], s[30:31]
	s_cbranch_execz .LBB0_228
	v_lshl_add_u32 v0, v0, 2, v255
	v_lshl_add_u64 v[194:195], v[216:217], 0, v[0:1]
	v_mov_b32_dpp v178, v174 row_shr:1 row_mask:0xf bank_mask:0x1
	v_mov_b32_dpp v179, v175 row_shr:1 row_mask:0xf bank_mask:0x1
	v_mov_b32_dpp v180, v176 row_shr:1 row_mask:0xf bank_mask:0x1
	v_mov_b32_dpp v181, v177 row_shr:1 row_mask:0xf bank_mask:0x1
	v_mov_b32_dpp v178, v170 row_shr:2 row_mask:0xf bank_mask:0x1
	v_mov_b32_dpp v179, v171 row_shr:2 row_mask:0xf bank_mask:0x1
	v_mov_b32_dpp v180, v172 row_shr:2 row_mask:0xf bank_mask:0x1
	v_mov_b32_dpp v181, v173 row_shr:2 row_mask:0xf bank_mask:0x1
	v_mov_b32_dpp v178, v134 row_shr:3 row_mask:0xf bank_mask:0x1
	v_mov_b32_dpp v179, v135 row_shr:3 row_mask:0xf bank_mask:0x1
	v_mov_b32_dpp v180, v136 row_shr:3 row_mask:0xf bank_mask:0x1
	v_mov_b32_dpp v181, v137 row_shr:3 row_mask:0xf bank_mask:0x1
	s_bitcmp1_b32 exec_lo, 15
	s_cbranch_scc0 .Lmy_exp_lo0
	v_mov_b32_dpp v178, v174 row_shl:1 row_mask:0xf bank_mask:0x8
	v_mov_b32_dpp v179, v175 row_shl:1 row_mask:0xf bank_mask:0x8
	v_mov_b32_dpp v180, v176 row_shl:1 row_mask:0xf bank_mask:0x8
	v_mov_b32_dpp v181, v177 row_shl:1 row_mask:0xf bank_mask:0x8
	v_mov_b32_dpp v178, v170 row_shl:2 row_mask:0xf bank_mask:0x8
	v_mov_b32_dpp v179, v171 row_shl:2 row_mask:0xf bank_mask:0x8
	v_mov_b32_dpp v180, v172 row_shl:2 row_mask:0xf bank_mask:0x8
	v_mov_b32_dpp v181, v173 row_shl:2 row_mask:0xf bank_mask:0x8
	v_mov_b32_dpp v178, v134 row_shl:3 row_mask:0xf bank_mask:0x8
	v_mov_b32_dpp v179, v135 row_shl:3 row_mask:0xf bank_mask:0x8
	v_mov_b32_dpp v180, v136 row_shl:3 row_mask:0xf bank_mask:0x8
	v_mov_b32_dpp v181, v137 row_shl:3 row_mask:0xf bank_mask:0x8
.Lmy_exp_lo0:
	global_store_dwordx4 v[194:195], v[178:181], off
.LBB0_228:
	s_or_b64 exec, exec, s[34:35]
	v_add_f32_e32 v0, v247, v248
	v_fmamk_f32 v0, v0, 0x3a800000, v219
	v_rsq_f32_e32 v0, v0
	s_add_i32 s25, s23, 0x80
	s_lshr_b32 s23, s25, 4
	v_cmp_lt_i32_e32 vcc, 11, v5
	v_pk_mul_f32 v[132:133], v[132:133], v[0:1] op_sel_hi:[1,0]
	v_pk_mul_f32 v[130:131], v[130:131], v[0:1] op_sel_hi:[1,0]
	v_pk_mul_f32 v[8:9], v[8:9], v[0:1] op_sel_hi:[1,0]
	v_pk_mul_f32 v[6:7], v[6:7], v[0:1] op_sel_hi:[1,0]
	v_pk_mul_f32 v[128:129], v[128:129], v[0:1] op_sel_hi:[1,0]
	v_pk_mul_f32 v[126:127], v[126:127], v[0:1] op_sel_hi:[1,0]
	v_pk_mul_f32 v[12:13], v[12:13], v[0:1] op_sel_hi:[1,0]
	v_pk_mul_f32 v[10:11], v[10:11], v[0:1] op_sel_hi:[1,0]
	v_add_f32_e32 v0, v245, v246
	v_fmamk_f32 v0, v0, 0x3a800000, v219
	v_rsq_f32_e32 v0, v0
	s_mov_b64 s[30:31], 0
	v_pk_mul_f32 v[124:125], v[124:125], v[0:1] op_sel_hi:[1,0]
	v_pk_mul_f32 v[122:123], v[122:123], v[0:1] op_sel_hi:[1,0]
	v_pk_mul_f32 v[16:17], v[16:17], v[0:1] op_sel_hi:[1,0]
	v_pk_mul_f32 v[14:15], v[14:15], v[0:1] op_sel_hi:[1,0]
	v_pk_mul_f32 v[120:121], v[120:121], v[0:1] op_sel_hi:[1,0]
	v_pk_mul_f32 v[118:119], v[118:119], v[0:1] op_sel_hi:[1,0]
	v_pk_mul_f32 v[28:29], v[28:29], v[0:1] op_sel_hi:[1,0]
	v_pk_mul_f32 v[26:27], v[26:27], v[0:1] op_sel_hi:[1,0]
	s_and_saveexec_b64 s[34:35], vcc
	s_xor_b64 s[34:35], exec, s[34:35]
	s_cbranch_execz .LBB0_234
	s_and_b32 s36, s25, 0xfc0
	s_cmpk_eq_i32 s36, 0xfc0
	s_cselect_b64 s[30:31], -1, 0
	s_lshr_b32 s25, s25, 11
	s_cmpk_lg_i32 s36, 0xfc0
	s_mul_i32 s36, s23, 0x1800
	v_add_u32_e32 v134, s36, v192
	v_lshl_add_u32 v0, v134, 2, v225
	v_add_u32_e32 v0, v0, v255
	v_lshl_add_u64 v[136:137], s[16:17], 0, v[0:1]
	v_mov_b32_e32 v178, v130
	v_mov_b32_e32 v179, v131
	v_mov_b32_e32 v180, v132
	v_mov_b32_e32 v181, v133
	v_mov_b32_dpp v178, v6 row_shl:1 row_mask:0xf bank_mask:0x8
	v_mov_b32_dpp v179, v7 row_shl:1 row_mask:0xf bank_mask:0x8
	v_mov_b32_dpp v180, v8 row_shl:1 row_mask:0xf bank_mask:0x8
	v_mov_b32_dpp v181, v9 row_shl:1 row_mask:0xf bank_mask:0x8
	v_mov_b32_dpp v178, v126 row_shl:2 row_mask:0xf bank_mask:0x8
	v_mov_b32_dpp v179, v127 row_shl:2 row_mask:0xf bank_mask:0x8
	v_mov_b32_dpp v180, v128 row_shl:2 row_mask:0xf bank_mask:0x8
	v_mov_b32_dpp v181, v129 row_shl:2 row_mask:0xf bank_mask:0x8
	v_mov_b32_dpp v178, v10 row_shl:3 row_mask:0xf bank_mask:0x8
	v_mov_b32_dpp v179, v11 row_shl:3 row_mask:0xf bank_mask:0x8
	v_mov_b32_dpp v180, v12 row_shl:3 row_mask:0xf bank_mask:0x8
	v_mov_b32_dpp v181, v13 row_shl:3 row_mask:0xf bank_mask:0x8
	global_store_dwordx4 v[136:137], v[178:181], off
	s_cbranch_scc1 .LBB0_231
	s_and_b32 s36, s25, 0x1ffffe
	s_mulk_i32 s36, 0x1800
	v_add_lshl_u32 v0, s36, v192, 2
	v_add_u32_e32 v0, v0, v255
	v_lshl_add_u64 v[136:137], s[18:19], 0, v[0:1]
	global_store_dwordx4 v[136:137], v[178:181], off
.LBB0_231:
	v_lshl_add_u32 v0, v134, 2, v226
	v_add_u32_e32 v0, v0, v255
	v_lshl_add_u64 v[134:135], s[16:17], 0, v[0:1]
	v_mov_b32_e32 v178, v122
	v_mov_b32_e32 v179, v123
	v_mov_b32_e32 v180, v124
	v_mov_b32_e32 v181, v125
	v_mov_b32_dpp v178, v14 row_shl:1 row_mask:0xf bank_mask:0x8
	v_mov_b32_dpp v179, v15 row_shl:1 row_mask:0xf bank_mask:0x8
	v_mov_b32_dpp v180, v16 row_shl:1 row_mask:0xf bank_mask:0x8
	v_mov_b32_dpp v181, v17 row_shl:1 row_mask:0xf bank_mask:0x8
	v_mov_b32_dpp v178, v118 row_shl:2 row_mask:0xf bank_mask:0x8
	v_mov_b32_dpp v179, v119 row_shl:2 row_mask:0xf bank_mask:0x8
	v_mov_b32_dpp v180, v120 row_shl:2 row_mask:0xf bank_mask:0x8
	v_mov_b32_dpp v181, v121 row_shl:2 row_mask:0xf bank_mask:0x8
	v_mov_b32_dpp v178, v26 row_shl:3 row_mask:0xf bank_mask:0x8
	v_mov_b32_dpp v179, v27 row_shl:3 row_mask:0xf bank_mask:0x8
	v_mov_b32_dpp v180, v28 row_shl:3 row_mask:0xf bank_mask:0x8
	v_mov_b32_dpp v181, v29 row_shl:3 row_mask:0xf bank_mask:0x8
	global_store_dwordx4 v[134:135], v[178:181], off
	s_andn2_b64 vcc, exec, s[30:31]
	s_mov_b64 s[30:31], 0
	s_cbranch_vccnz .LBB0_233
	s_mulk_i32 s25, 0x1800
	v_add_u32_e32 v0, s25, v192
	s_mov_b64 s[30:31], -1

.LBB0_234:
	s_or_saveexec_b64 s[34:35], s[34:35]
	v_add_f32_e32 v134, v243, v244
	v_fmamk_f32 v134, v134, 0x3a800000, v219
	v_rsq_f32_e32 v170, v134
	v_mov_b64_e32 v[176:177], v[16:17]
	v_mov_b64_e32 v[180:181], v[124:125]
	v_mov_b64_e32 v[216:217], s[18:19]
	v_pk_mul_f32 v[136:137], v[116:117], v[170:171] op_sel_hi:[1,0]
	v_pk_mul_f32 v[116:117], v[48:49], v[170:171] op_sel_hi:[1,0]
	v_add_f32_e32 v48, v241, v242
	v_fmamk_f32 v48, v48, 0x3a800000, v219
	v_rsq_f32_e32 v172, v48
	v_pk_mul_f32 v[134:135], v[114:115], v[170:171] op_sel_hi:[1,0]
	v_pk_mul_f32 v[40:41], v[40:41], v[170:171] op_sel_hi:[1,0]
	v_pk_mul_f32 v[38:39], v[38:39], v[170:171] op_sel_hi:[1,0]
	v_pk_mul_f32 v[114:115], v[46:47], v[170:171] op_sel_hi:[1,0]
	v_pk_mul_f32 v[48:49], v[44:45], v[170:171] op_sel_hi:[1,0]
	v_pk_mul_f32 v[46:47], v[42:43], v[170:171] op_sel_hi:[1,0]
	v_pk_mul_f32 v[112:113], v[112:113], v[172:173] op_sel_hi:[1,0]
	v_pk_mul_f32 v[110:111], v[110:111], v[172:173] op_sel_hi:[1,0]
	v_pk_mul_f32 v[44:45], v[108:109], v[172:173] op_sel_hi:[1,0]
	v_pk_mul_f32 v[42:43], v[106:107], v[172:173] op_sel_hi:[1,0]
	v_pk_mul_f32 v[104:105], v[104:105], v[172:173] op_sel_hi:[1,0]
	v_pk_mul_f32 v[102:103], v[102:103], v[172:173] op_sel_hi:[1,0]
	v_pk_mul_f32 v[52:53], v[52:53], v[172:173] op_sel_hi:[1,0]
	v_pk_mul_f32 v[50:51], v[50:51], v[172:173] op_sel_hi:[1,0]
	v_mov_b64_e32 v[108:109], v[28:29]
	v_mov_b64_e32 v[172:173], v[120:121]
	v_mov_b64_e32 v[106:107], v[26:27]
	v_mov_b64_e32 v[170:171], v[118:119]
	v_mov_b64_e32 v[174:175], v[14:15]
	v_mov_b64_e32 v[178:179], v[122:123]
	s_xor_b64 exec, exec, s[34:35]
	s_cbranch_execz .LBB0_238
	v_cmp_gt_u32_e32 vcc, 4, v5
	s_mov_b64 s[38:39], s[30:31]
	s_and_saveexec_b64 s[36:37], vcc
	s_cbranch_execz .LBB0_237
	s_mulk_i32 s23, 0x1800
	v_add_u32_e32 v108, s23, v192
	v_lshl_add_u32 v0, v108, 2, v255
	v_lshl_add_u64 v[106:107], s[16:17], 0, v[0:1]
	v_mov_b32_e32 v194, v134
	v_mov_b32_e32 v195, v135
	v_mov_b32_e32 v196, v136
	v_mov_b32_e32 v197, v137
	v_mov_b32_dpp v194, v38 row_shr:1 row_mask:0xf bank_mask:0x1
	v_mov_b32_dpp v195, v39 row_shr:1 row_mask:0xf bank_mask:0x1
	v_mov_b32_dpp v196, v40 row_shr:1 row_mask:0xf bank_mask:0x1
	v_mov_b32_dpp v197, v41 row_shr:1 row_mask:0xf bank_mask:0x1
	v_mov_b32_dpp v194, v114 row_shr:2 row_mask:0xf bank_mask:0x1
	v_mov_b32_dpp v195, v115 row_shr:2 row_mask:0xf bank_mask:0x1
	v_mov_b32_dpp v196, v116 row_shr:2 row_mask:0xf bank_mask:0x1
	v_mov_b32_dpp v197, v117 row_shr:2 row_mask:0xf bank_mask:0x1
	v_mov_b32_dpp v194, v46 row_shr:3 row_mask:0xf bank_mask:0x1
	v_mov_b32_dpp v195, v47 row_shr:3 row_mask:0xf bank_mask:0x1
	v_mov_b32_dpp v196, v48 row_shr:3 row_mask:0xf bank_mask:0x1
	v_mov_b32_dpp v197, v49 row_shr:3 row_mask:0xf bank_mask:0x1
	v_add_u32_e32 v0, 0x1800, v108
	s_or_b64 s[38:39], s[30:31], exec
	global_store_dwordx4 v[106:107], v[194:197], off

.LBB0_238:
	s_or_b64 exec, exec, s[34:35]
	s_and_saveexec_b64 s[34:35], s[30:31]
	s_cbranch_execz .LBB0_240
	v_lshl_add_u32 v0, v0, 2, v255
	v_lshl_add_u64 v[194:195], v[216:217], 0, v[0:1]
	v_mov_b32_dpp v178, v174 row_shr:1 row_mask:0xf bank_mask:0x1
	v_mov_b32_dpp v179, v175 row_shr:1 row_mask:0xf bank_mask:0x1
	v_mov_b32_dpp v180, v176 row_shr:1 row_mask:0xf bank_mask:0x1
	v_mov_b32_dpp v181, v177 row_shr:1 row_mask:0xf bank_mask:0x1
	v_mov_b32_dpp v178, v170 row_shr:2 row_mask:0xf bank_mask:0x1
	v_mov_b32_dpp v179, v171 row_shr:2 row_mask:0xf bank_mask:0x1
	v_mov_b32_dpp v180, v172 row_shr:2 row_mask:0xf bank_mask:0x1
	v_mov_b32_dpp v181, v173 row_shr:2 row_mask:0xf bank_mask:0x1
	v_mov_b32_dpp v178, v106 row_shr:3 row_mask:0xf bank_mask:0x1
	v_mov_b32_dpp v179, v107 row_shr:3 row_mask:0xf bank_mask:0x1
	v_mov_b32_dpp v180, v108 row_shr:3 row_mask:0xf bank_mask:0x1
	v_mov_b32_dpp v181, v109 row_shr:3 row_mask:0xf bank_mask:0x1
	s_bitcmp1_b32 exec_lo, 15
	s_cbranch_scc0 .Lmy_exp_lo1
	v_mov_b32_dpp v178, v174 row_shl:1 row_mask:0xf bank_mask:0x8
	v_mov_b32_dpp v179, v175 row_shl:1 row_mask:0xf bank_mask:0x8
	v_mov_b32_dpp v180, v176 row_shl:1 row_mask:0xf bank_mask:0x8
	v_mov_b32_dpp v181, v177 row_shl:1 row_mask:0xf bank_mask:0x8
	v_mov_b32_dpp v178, v170 row_shl:2 row_mask:0xf bank_mask:0x8
	v_mov_b32_dpp v179, v171 row_shl:2 row_mask:0xf bank_mask:0x8
	v_mov_b32_dpp v180, v172 row_shl:2 row_mask:0xf bank_mask:0x8
	v_mov_b32_dpp v181, v173 row_shl:2 row_mask:0xf bank_mask:0x8
	v_mov_b32_dpp v178, v106 row_shl:3 row_mask:0xf bank_mask:0x8
	v_mov_b32_dpp v179, v107 row_shl:3 row_mask:0xf bank_mask:0x8
	v_mov_b32_dpp v180, v108 row_shl:3 row_mask:0xf bank_mask:0x8
	v_mov_b32_dpp v181, v109 row_shl:3 row_mask:0xf bank_mask:0x8
